# grid-barrier spin loops poll without s_sleep 1 (28 sites), on top of saddr + norm-loop gain-load hoist version
# baseline (speedup 1.0000x reference)
.LBB0_71:
	global_load_dword v17, v18, s[6:7] sc1
	s_waitcnt lgkmcnt(0)
	global_load_dword v2, v18, s[12:13] sc1
	global_load_dword v3, v18, s[14:15] sc1
	global_load_dword v4, v18, s[16:17] sc1
	global_load_dword v5, v18, s[18:19] sc1
	global_load_dword v6, v18, s[20:21] sc1
	global_load_dword v7, v18, s[22:23] sc1
	global_load_dword v8, v18, s[24:25] sc1
	global_load_dword v9, v18, s[26:27] sc1
	global_load_dword v10, v18, s[28:29] sc1
	global_load_dword v11, v18, s[30:31] sc1
	global_load_dword v12, v18, s[34:35] sc1
	global_load_dword v13, v18, s[36:37] sc1
	global_load_dword v14, v18, s[38:39] sc1
	global_load_dword v15, v18, s[40:41] sc1
	global_load_dword v16, v18, s[42:43] sc1
	s_mov_b64 s[46:47], -1
	s_mov_b64 s[48:49], -1
	s_waitcnt vmcnt(14)
	v_add_u32_e32 v19, v2, v17
	s_waitcnt vmcnt(13)
	v_add_u32_e32 v19, v19, v3
	s_waitcnt vmcnt(12)
	v_add_u32_e32 v19, v19, v4
	s_waitcnt vmcnt(11)
	v_add_u32_e32 v19, v19, v5
	s_waitcnt vmcnt(10)
	v_add_u32_e32 v19, v19, v6
	s_waitcnt vmcnt(9)
	v_add_u32_e32 v19, v19, v7
	s_waitcnt vmcnt(8)
	v_add_u32_e32 v19, v19, v8
	s_waitcnt vmcnt(7)
	v_add_u32_e32 v19, v19, v9
	s_waitcnt vmcnt(6)
	v_add_u32_e32 v19, v19, v10
	s_waitcnt vmcnt(5)
	v_add_u32_e32 v19, v19, v11
	s_waitcnt vmcnt(4)
	v_add_u32_e32 v19, v19, v12
	s_waitcnt vmcnt(3)
	v_add_u32_e32 v19, v19, v13
	s_waitcnt vmcnt(2)
	v_add_u32_e32 v19, v19, v14
	s_waitcnt vmcnt(1)
	v_add_u32_e32 v19, v19, v15
	s_waitcnt vmcnt(0)
	v_add_u32_e32 v19, v19, v16
	v_cmp_eq_u32_e32 vcc, s3, v19
	s_cbranch_vccnz .LBB0_70
	s_and_b32 s46, s33, 0xff
	s_cmp_eq_u32 s46, 0
	s_mov_b64 s[46:47], -1
	s_mov_b64 s[62:63], -1
	s_cbranch_scc0 .LBB0_75
	global_load_dword v19, v18, s[4:5] sc1
	s_waitcnt vmcnt(0)
	v_cmp_eq_u32_e32 vcc, 0, v19
	s_cbranch_vccnz .LBB0_77
	s_mov_b64 s[62:63], 0

.LBB0_89:
	s_and_b32 s24, s3, 0xff
	s_mov_b64 s[22:23], -1
	s_cmp_lg_u32 s24, 0
	s_mov_b64 s[26:27], -1
	s_cbranch_scc1 .LBB0_92
	global_load_dword v4, v2, s[14:15] sc1
	s_waitcnt vmcnt(0)
	v_cmp_eq_u32_e32 vcc, 0, v4
	s_cbranch_vccnz .LBB0_94
	s_mov_b64 s[26:27], 0
	s_mov_b64 s[24:25], -1

.LBB0_106:
	s_and_b32 s22, s3, 0xff
	s_cmp_lg_u32 s22, 0
	s_mov_b64 s[24:25], -1
	s_cbranch_scc1 .LBB0_109
	global_load_dword v3, v2, s[14:15] sc1
	s_waitcnt vmcnt(0)
	v_cmp_eq_u32_e32 vcc, 0, v3
	s_cbranch_vccnz .LBB0_111
	s_mov_b64 s[24:25], 0
	s_mov_b64 s[22:23], -1

.LBB0_128:
	global_load_dword v2, v0, s[4:5] offset:32 sc1
	s_waitcnt vmcnt(0)
	v_and_b32_e32 v2, 0xffff0000, v2
	v_cmp_ne_u32_e32 vcc, v2, v1
	s_or_b64 s[6:7], vcc, s[6:7]
	s_andn2_b64 exec, exec, s[6:7]
	s_cbranch_execnz .LBB0_128

.LBB0_203:
	v_readlane_b32 s4, v253, 21
	v_readlane_b32 s5, v253, 22
	s_waitcnt lgkmcnt(0)
	global_load_dword v0, v161, s[62:63] sc1
	s_mov_b64 s[18:19], -1
	s_mov_b64 s[24:25], -1
	s_nop 0
	global_load_dword v1, v161, s[4:5] sc1
	v_readlane_b32 s4, v253, 23
	v_readlane_b32 s5, v253, 24
	s_waitcnt vmcnt(0)
	v_add_u32_e32 v16, v1, v0
	s_nop 2
	global_load_dword v2, v161, s[4:5] sc1
	v_readlane_b32 s4, v253, 25
	v_readlane_b32 s5, v253, 26
	s_waitcnt vmcnt(0)
	v_add_u32_e32 v16, v16, v2
	s_nop 2
	global_load_dword v3, v161, s[4:5] sc1
	v_readlane_b32 s4, v253, 27
	v_readlane_b32 s5, v253, 28
	s_waitcnt vmcnt(0)
	v_add_u32_e32 v16, v16, v3
	s_nop 2
	global_load_dword v4, v161, s[4:5] sc1
	v_readlane_b32 s4, v253, 29
	v_readlane_b32 s5, v253, 30
	s_waitcnt vmcnt(0)
	v_add_u32_e32 v16, v16, v4
	s_nop 2
	global_load_dword v5, v161, s[4:5] sc1
	v_readlane_b32 s4, v253, 31
	v_readlane_b32 s5, v253, 32
	s_waitcnt vmcnt(0)
	v_add_u32_e32 v16, v16, v5
	s_nop 2
	global_load_dword v6, v161, s[4:5] sc1
	v_readlane_b32 s4, v253, 33
	v_readlane_b32 s5, v253, 34
	s_waitcnt vmcnt(0)
	v_add_u32_e32 v16, v16, v6
	s_nop 2
	global_load_dword v7, v161, s[4:5] sc1
	v_readlane_b32 s4, v253, 35
	v_readlane_b32 s5, v253, 36
	s_waitcnt vmcnt(0)
	v_add_u32_e32 v16, v16, v7
	s_nop 2
	global_load_dword v8, v161, s[4:5] sc1
	v_readlane_b32 s4, v253, 37
	v_readlane_b32 s5, v253, 38
	s_waitcnt vmcnt(0)
	v_add_u32_e32 v16, v16, v8
	s_nop 2
	global_load_dword v9, v161, s[4:5] sc1
	v_readlane_b32 s4, v253, 39
	v_readlane_b32 s5, v253, 40
	s_waitcnt vmcnt(0)
	v_add_u32_e32 v16, v16, v9
	s_nop 2
	global_load_dword v10, v161, s[4:5] sc1
	v_readlane_b32 s4, v253, 41
	v_readlane_b32 s5, v253, 42
	s_waitcnt vmcnt(0)
	v_add_u32_e32 v16, v16, v10
	s_nop 2
	global_load_dword v11, v161, s[4:5] sc1
	v_readlane_b32 s4, v253, 43
	v_readlane_b32 s5, v253, 44
	s_waitcnt vmcnt(0)
	v_add_u32_e32 v16, v16, v11
	s_nop 2
	global_load_dword v12, v161, s[4:5] sc1
	v_readlane_b32 s4, v253, 45
	v_readlane_b32 s5, v253, 46
	s_waitcnt vmcnt(0)
	v_add_u32_e32 v16, v16, v12
	s_nop 2
	global_load_dword v13, v161, s[4:5] sc1
	v_readlane_b32 s4, v253, 47
	v_readlane_b32 s5, v253, 48
	s_waitcnt vmcnt(0)
	v_add_u32_e32 v16, v16, v13
	s_nop 2
	global_load_dword v14, v161, s[4:5] sc1
	v_readlane_b32 s4, v253, 49
	v_readlane_b32 s5, v253, 50
	s_waitcnt vmcnt(0)
	v_add_u32_e32 v16, v16, v14
	s_nop 2
	global_load_dword v15, v161, s[4:5] sc1
	s_waitcnt vmcnt(0)
	v_add_u32_e32 v16, v16, v15
	v_cmp_eq_u32_e32 vcc, s83, v16
	s_cbranch_vccnz .LBB0_202
	s_and_b32 s1, s0, 0xff
	s_cmp_eq_u32 s1, 0
	s_mov_b64 s[34:35], -1
	s_cbranch_scc0 .LBB0_207
	global_load_dword v16, v161, s[96:97] sc1
	s_waitcnt vmcnt(0)
	v_cmp_eq_u32_e32 vcc, 0, v16
	s_cbranch_vccnz .LBB0_209
	s_mov_b64 s[34:35], 0

.LBB0_221:
	s_and_b32 s1, s0, 0xff
	s_mov_b64 s[38:39], -1
	s_cmp_lg_u32 s1, 0
	s_mov_b64 s[84:85], -1
	s_cbranch_scc1 .LBB0_224
	global_load_dword v0, v161, s[96:97] sc1
	s_waitcnt vmcnt(0)
	v_cmp_eq_u32_e32 vcc, 0, v0
	s_cbranch_vccnz .LBB0_226
	s_mov_b64 s[84:85], 0
	s_mov_b64 s[64:65], -1

.LBB0_278:
	s_and_b32 s1, s0, 0xff
	s_mov_b64 s[38:39], -1
	s_cmp_lg_u32 s1, 0
	s_mov_b64 s[64:65], -1
	s_cbranch_scc1 .LBB0_281
	global_load_dword v0, v161, s[96:97] sc1
	s_waitcnt vmcnt(0)
	v_cmp_eq_u32_e32 vcc, 0, v0
	s_cbranch_vccnz .LBB0_283
	s_mov_b64 s[64:65], 0
	s_mov_b64 s[40:41], -1

.LBB0_607:
	v_readlane_b32 s4, v253, 21
	v_readlane_b32 s5, v253, 22
	global_load_dword v0, v1, s[62:63] sc1
	s_mov_b64 s[24:25], -1
	s_mov_b64 s[34:35], -1
	s_waitcnt lgkmcnt(0)
	s_nop 0
	global_load_dword v2, v1, s[4:5] sc1
	v_readlane_b32 s4, v253, 23
	v_readlane_b32 s5, v253, 24
	s_waitcnt vmcnt(0)
	v_add_u32_e32 v17, v2, v0
	s_nop 2
	global_load_dword v3, v1, s[4:5] sc1
	v_readlane_b32 s4, v253, 25
	v_readlane_b32 s5, v253, 26
	s_waitcnt vmcnt(0)
	v_add_u32_e32 v17, v17, v3
	s_nop 2
	global_load_dword v4, v1, s[4:5] sc1
	v_readlane_b32 s4, v253, 27
	v_readlane_b32 s5, v253, 28
	s_waitcnt vmcnt(0)
	v_add_u32_e32 v17, v17, v4
	s_nop 2
	global_load_dword v5, v1, s[4:5] sc1
	v_readlane_b32 s4, v253, 29
	v_readlane_b32 s5, v253, 30
	s_waitcnt vmcnt(0)
	v_add_u32_e32 v17, v17, v5
	s_nop 2
	global_load_dword v6, v1, s[4:5] sc1
	v_readlane_b32 s4, v253, 31
	v_readlane_b32 s5, v253, 32
	s_waitcnt vmcnt(0)
	v_add_u32_e32 v17, v17, v6
	s_nop 2
	global_load_dword v7, v1, s[4:5] sc1
	v_readlane_b32 s4, v253, 33
	v_readlane_b32 s5, v253, 34
	s_waitcnt vmcnt(0)
	v_add_u32_e32 v17, v17, v7
	s_nop 2
	global_load_dword v8, v1, s[4:5] sc1
	v_readlane_b32 s4, v253, 35
	v_readlane_b32 s5, v253, 36
	s_waitcnt vmcnt(0)
	v_add_u32_e32 v17, v17, v8
	s_nop 2
	global_load_dword v9, v1, s[4:5] sc1
	v_readlane_b32 s4, v253, 37
	v_readlane_b32 s5, v253, 38
	s_waitcnt vmcnt(0)
	v_add_u32_e32 v17, v17, v9
	s_nop 2
	global_load_dword v10, v1, s[4:5] sc1
	v_readlane_b32 s4, v253, 39
	v_readlane_b32 s5, v253, 40
	s_waitcnt vmcnt(0)
	v_add_u32_e32 v17, v17, v10
	s_nop 2
	global_load_dword v11, v1, s[4:5] sc1
	v_readlane_b32 s4, v253, 41
	v_readlane_b32 s5, v253, 42
	s_waitcnt vmcnt(0)
	v_add_u32_e32 v17, v17, v11
	s_nop 2
	global_load_dword v12, v1, s[4:5] sc1
	v_readlane_b32 s4, v253, 43
	v_readlane_b32 s5, v253, 44
	s_waitcnt vmcnt(0)
	v_add_u32_e32 v17, v17, v12
	s_nop 2
	global_load_dword v13, v1, s[4:5] sc1
	v_readlane_b32 s4, v253, 45
	v_readlane_b32 s5, v253, 46
	s_waitcnt vmcnt(0)
	v_add_u32_e32 v17, v17, v13
	s_nop 2
	global_load_dword v14, v1, s[4:5] sc1
	v_readlane_b32 s4, v253, 47
	v_readlane_b32 s5, v253, 48
	s_waitcnt vmcnt(0)
	v_add_u32_e32 v17, v17, v14
	s_nop 2
	global_load_dword v15, v1, s[4:5] sc1
	v_readlane_b32 s4, v253, 49
	v_readlane_b32 s5, v253, 50
	s_waitcnt vmcnt(0)
	v_add_u32_e32 v17, v17, v15
	s_nop 2
	global_load_dword v16, v1, s[4:5] sc1
	s_waitcnt vmcnt(0)
	v_add_u32_e32 v17, v17, v16
	v_cmp_eq_u32_e32 vcc, s83, v17
	s_cbranch_vccnz .LBB0_606
	s_and_b32 s1, s0, 0xff
	s_cmp_eq_u32 s1, 0
	s_mov_b64 s[36:37], -1
	s_cbranch_scc0 .LBB0_611
	global_load_dword v17, v1, s[96:97] sc1
	s_waitcnt vmcnt(0)
	v_cmp_eq_u32_e32 vcc, 0, v17
	s_cbranch_vccnz .LBB0_613
	s_mov_b64 s[36:37], 0

.LBB0_625:
	s_and_b32 s1, s0, 0xff
	s_mov_b64 s[40:41], -1
	s_cmp_lg_u32 s1, 0
	s_mov_b64 s[48:49], -1
	s_cbranch_scc1 .LBB0_628
	global_load_dword v2, v1, s[96:97] sc1
	s_waitcnt vmcnt(0)
	v_cmp_eq_u32_e32 vcc, 0, v2
	s_cbranch_vccnz .LBB0_630
	s_mov_b64 s[48:49], 0
	s_mov_b64 s[44:45], -1
